# vAA + final RMSNorm loop software-pipelined: gain vector hoisted out of the loop, rows double-buffered (next row's 5 loads issued before the current row is reduced/scaled/stored)
# speedup vs baseline: 1.0051x; 1.0051x over previous
.LBB0_1007:
	global_load_dwordx4 v[34:37], v[0:1], off
	global_load_dwordx4 v[38:41], v[0:1], off offset:1024
	global_load_dwordx4 v[42:45], v[0:1], off offset:2048
	global_load_dwordx4 v[46:49], v[0:1], off offset:3072
	global_load_dword v11, v[2:3], off
	global_load_dwordx4 v[12:15], v[4:5], off offset:-3072
	global_load_dwordx4 v[16:19], v[4:5], off offset:-2048
	global_load_dwordx4 v[20:23], v[4:5], off offset:-1024
	global_load_dwordx4 v[50:53], v[4:5], off
.Lfn_loop:
	s_add_i32 s8, s8, s68
	s_cmpk_gt_i32 s8, 0x3fff
	s_cselect_b32 s10, 0, s0
	s_cselect_b32 s11, 0, s1
	s_cselect_b32 s12, 0, s2
	s_cselect_b32 s13, 0, s3
	s_cselect_b64 s[14:15], -1, 0
	v_lshl_add_u64 v[74:75], v[2:3], 0, s[10:11]
	v_lshl_add_u64 v[72:73], v[4:5], 0, s[12:13]
	global_load_dword v54, v[74:75], off
	global_load_dwordx4 v[56:59], v[72:73], off offset:-3072
	global_load_dwordx4 v[60:63], v[72:73], off offset:-2048
	global_load_dwordx4 v[64:67], v[72:73], off offset:-1024
	global_load_dwordx4 v[68:71], v[72:73], off
	s_waitcnt vmcnt(9)
	ds_bpermute_b32 v24, v6, v11
	s_waitcnt lgkmcnt(0)
	v_add_f32_e32 v11, v11, v24
	ds_bpermute_b32 v24, v7, v11
	s_waitcnt lgkmcnt(0)
	v_add_f32_e32 v11, v11, v24
	ds_bpermute_b32 v24, v8, v11
	s_waitcnt lgkmcnt(0)
	v_add_f32_e32 v11, v11, v24
	ds_bpermute_b32 v24, v9, v11
	s_waitcnt lgkmcnt(0)
	v_add_f32_e32 v11, v11, v24
	v_fmamk_f32 v11, v11, 0x3a800000, v10
	v_mul_f32_e32 v24, 0x4b800000, v11
	v_cmp_gt_f32_e32 vcc, s4, v11
	s_nop 1
	v_cndmask_b32_e32 v11, v11, v24, vcc
	v_rsq_f32_e32 v11, v11
	s_nop 0
	v_mul_f32_e32 v24, 0x45800000, v11
	v_cndmask_b32_e32 v24, v11, v24, vcc
	s_waitcnt vmcnt(8)
	v_pk_mul_f32 v[12:13], v[24:25], v[12:13] op_sel_hi:[0,1]
	v_pk_mul_f32 v[14:15], v[24:25], v[14:15] op_sel_hi:[0,1]
	v_pk_mul_f32 v[14:15], v[14:15], v[36:37]
	v_pk_mul_f32 v[12:13], v[12:13], v[34:35]
	global_store_dwordx4 v[4:5], v[12:15], off offset:-3072
	s_waitcnt vmcnt(8)
	v_pk_mul_f32 v[16:17], v[24:25], v[16:17] op_sel_hi:[0,1]
	v_pk_mul_f32 v[18:19], v[24:25], v[18:19] op_sel_hi:[0,1]
	v_pk_mul_f32 v[18:19], v[18:19], v[40:41]
	v_pk_mul_f32 v[16:17], v[16:17], v[38:39]
	global_store_dwordx4 v[4:5], v[16:19], off offset:-2048
	s_waitcnt vmcnt(8)
	v_pk_mul_f32 v[20:21], v[24:25], v[20:21] op_sel_hi:[0,1]
	v_pk_mul_f32 v[22:23], v[24:25], v[22:23] op_sel_hi:[0,1]
	v_pk_mul_f32 v[22:23], v[22:23], v[44:45]
	v_pk_mul_f32 v[20:21], v[20:21], v[42:43]
	global_store_dwordx4 v[4:5], v[20:23], off offset:-1024
	s_waitcnt vmcnt(8)
	v_pk_mul_f32 v[50:51], v[24:25], v[50:51] op_sel_hi:[0,1]
	v_pk_mul_f32 v[52:53], v[24:25], v[52:53] op_sel_hi:[0,1]
	v_pk_mul_f32 v[52:53], v[52:53], v[48:49]
	v_pk_mul_f32 v[50:51], v[50:51], v[46:47]
	global_store_dwordx4 v[4:5], v[50:53], off
	s_and_b64 vcc, exec, s[14:15]
	s_cbranch_vccnz .Lfn_done
	s_add_i32 s8, s8, s68
	s_cmpk_gt_i32 s8, 0x3fff
	s_cselect_b32 s10, 0, s0
	s_cselect_b32 s11, 0, s1
	s_cselect_b32 s12, 0, s2
	s_cselect_b32 s13, 0, s3
	s_cselect_b64 s[14:15], -1, 0
	v_lshl_add_u64 v[2:3], v[74:75], 0, s[10:11]
	v_lshl_add_u64 v[4:5], v[72:73], 0, s[12:13]
	global_load_dword v11, v[2:3], off
	global_load_dwordx4 v[12:15], v[4:5], off offset:-3072
	global_load_dwordx4 v[16:19], v[4:5], off offset:-2048
	global_load_dwordx4 v[20:23], v[4:5], off offset:-1024
	global_load_dwordx4 v[50:53], v[4:5], off
	s_waitcnt vmcnt(9)
	ds_bpermute_b32 v24, v6, v54
	s_waitcnt lgkmcnt(0)
	v_add_f32_e32 v54, v54, v24
	ds_bpermute_b32 v24, v7, v54
	s_waitcnt lgkmcnt(0)
	v_add_f32_e32 v54, v54, v24
	ds_bpermute_b32 v24, v8, v54
	s_waitcnt lgkmcnt(0)
	v_add_f32_e32 v54, v54, v24
	ds_bpermute_b32 v24, v9, v54
	s_waitcnt lgkmcnt(0)
	v_add_f32_e32 v54, v54, v24
	v_fmamk_f32 v54, v54, 0x3a800000, v10
	v_mul_f32_e32 v24, 0x4b800000, v54
	v_cmp_gt_f32_e32 vcc, s4, v54
	s_nop 1
	v_cndmask_b32_e32 v54, v54, v24, vcc
	v_rsq_f32_e32 v54, v54
	s_nop 0
	v_mul_f32_e32 v24, 0x45800000, v54
	v_cndmask_b32_e32 v24, v54, v24, vcc
	s_waitcnt vmcnt(8)
	v_pk_mul_f32 v[56:57], v[24:25], v[56:57] op_sel_hi:[0,1]
	v_pk_mul_f32 v[58:59], v[24:25], v[58:59] op_sel_hi:[0,1]
	v_pk_mul_f32 v[58:59], v[58:59], v[36:37]
	v_pk_mul_f32 v[56:57], v[56:57], v[34:35]
	global_store_dwordx4 v[72:73], v[56:59], off offset:-3072
	s_waitcnt vmcnt(8)
	v_pk_mul_f32 v[60:61], v[24:25], v[60:61] op_sel_hi:[0,1]
	v_pk_mul_f32 v[62:63], v[24:25], v[62:63] op_sel_hi:[0,1]
	v_pk_mul_f32 v[62:63], v[62:63], v[40:41]
	v_pk_mul_f32 v[60:61], v[60:61], v[38:39]
	global_store_dwordx4 v[72:73], v[60:63], off offset:-2048
	s_waitcnt vmcnt(8)
	v_pk_mul_f32 v[64:65], v[24:25], v[64:65] op_sel_hi:[0,1]
	v_pk_mul_f32 v[66:67], v[24:25], v[66:67] op_sel_hi:[0,1]
	v_pk_mul_f32 v[66:67], v[66:67], v[44:45]
	v_pk_mul_f32 v[64:65], v[64:65], v[42:43]
	global_store_dwordx4 v[72:73], v[64:67], off offset:-1024
	s_waitcnt vmcnt(8)
	v_pk_mul_f32 v[68:69], v[24:25], v[68:69] op_sel_hi:[0,1]
	v_pk_mul_f32 v[70:71], v[24:25], v[70:71] op_sel_hi:[0,1]
	v_pk_mul_f32 v[70:71], v[70:71], v[48:49]
	v_pk_mul_f32 v[68:69], v[68:69], v[46:47]
	global_store_dwordx4 v[72:73], v[68:71], off
	s_and_b64 vcc, exec, s[14:15]
	s_cbranch_vccz .Lfn_loop
.Lfn_done:
.LBB0_1008:
	s_endpgm
